# GEMM prologues: K-tile 1 half-tiles staged together with K-tile 0 (first wait vmcnt(8) after all 14 DMAs instead of vmcnt(2) between the two groups)
# baseline (speedup 1.0000x reference)
; #define PG8_STAGE(bufoff, gbase, voff) do { _Pragma("unroll") for (int _i = 0; _i < 2; ++_i) \
;         __builtin_amdgcn_global_load_lds((const unsigned*)((const char*)(gbase) + (voff)[_i]), (PG8_LAS unsigned*)(lds + (bufoff) + ldsw + _i * 8192), 16, 0, 0); } while (0)
; #define PG8_WAIT_V(n) asm volatile("s_waitcnt vmcnt(" #n ")" ::: "memory")
; #define PG8_BAR __builtin_amdgcn_s_barrier()
; template <class Epi, class Sched, bool ALIGN_EPI = false, bool SP2 = false>
; __device__ __forceinline__ void gemm_phase(PG8_LAS unsigned char* lds, const Gemm g, const Sched& S, const Epi& E) {
;     ...
;     for (int i = 0; i < 2; ++i) { int R, C; stage_rc(tid * 16 + i * 8192, R, C); const int Rb = Epi::PERM ? ((R & ~31) + perm32(R & 31)) : R;
;         voffA[i] = (unsigned)(R * K + C) * 2u; voffB[i] = (unsigned)(Rb * K + C) * 2u; }
;     const size_t kstep = (size_t)(BK * 2);
;     const size_t hstep = (size_t)HALF * K * 2;
;     const size_t tstep = 2 * hstep;
;     const unsigned ldsw = (unsigned)wid * 1024u;
;     const int aoff = lds_byte(wr * 64 + fr, fq * 8), boff = lds_byte(wc * 32 + fr, fq * 8);
;     ...
;     if constexpr (SP2) {
;         PG8_STAGE(PG8_SB(0, 0), cB, voffB); PG8_STAGE(PG8_SB(0, 1), cB + hstep, voffB); PG8_STAGE(PG8_SA(0, 0), cA, voffA); PG8_STAGE(PG8_SA(0, 1), cA + hstep, voffA);
;         if (wr == 1) PG8_BAR;
;         PG8_WAIT_V(2); PG8_BAR;
;         PG8_STAGE(PG8_SB(1, 0), cB + kstep, voffB); PG8_STAGE(PG8_SA(1, 0), cA + kstep, voffA); PG8_STAGE(PG8_SB(1, 1), cB + hstep + kstep, voffB);
;         PG8_WAIT_V(6); PG8_BAR;
.LBB11_218:
	s_lshl_b32 s6, s6, 5
	s_and_b32 s14, s6, 0x60
	v_readlane_b32 s6, v249, 37
	s_ashr_i32 s47, s6, 31
	s_mov_b64 s[6:7], 0x80
	s_add_i32 m0, s27, 0x18000
	v_lshl_add_u64 v[4:5], v[4:5], 0, s[6:7]
	s_lshl_b32 s11, s10, 13
	s_lshl_b32 s15, s14, 7
	global_load_lds_dwordx4 v[4:5], off
	v_lshl_add_u64 v[4:5], v[6:7], 0, s[6:7]
	s_add_i32 m0, s27, 0x1a000
	s_add_i32 s48, s27, 0x8000
	s_add_i32 s49, s27, 0xa000
	global_load_lds_dwordx4 v[4:5], off
	v_lshl_add_u64 v[4:5], v[8:9], 0, s[6:7]
	s_mov_b32 m0, s48
	s_add_u32 s12, s30, 0x80080
	global_load_lds_dwordx4 v[4:5], off
	v_lshl_add_u64 v[4:5], v[10:11], 0, s[6:7]
	s_mov_b32 m0, s49
	s_addc_u32 s13, s31, 0
	global_load_lds_dwordx4 v[4:5], off
	s_add_i32 m0, s27, 0x1c000
	v_lshl_add_u64 v[4:5], s[12:13], 0, v[134:135]
	global_load_lds_dwordx4 v[4:5], off
	v_lshl_add_u64 v[4:5], s[12:13], 0, v[130:131]
	s_add_i32 m0, s27, 0x1e000
	s_mov_b64 s[12:13], 0x5c200000
	global_load_lds_dwordx4 v[4:5], off
	s_waitcnt vmcnt(8)
	s_barrier
	v_lshl_add_u64 v[138:139], v[2:3], 0, s[12:13]
	v_lshrrev_b32_e32 v3, 1, v12
	v_and_b32_e32 v3, 24, v3
	v_and_b32_e32 v2, 15, v12
	v_lshlrev_b32_e32 v4, 1, v3
	v_lshl_or_b32 v146, s10, 6, v2
	v_lshl_or_b32 v2, v2, 6, v4
	v_lshlrev_b32_e32 v4, 2, v12
	v_and_b32_e32 v4, 32, v4
	v_bitop3_b32 v5, v2, s11, v4 bitop3:0xde
	v_bitop3_b32 v147, v2, s15, v4 bitop3:0xde
	v_lshlrev_b32_e32 v2, 15, v17
	v_and_b32_e32 v2, 0xffff0000, v2
	v_or_b32_e32 v148, s14, v3
	v_lshl_add_u32 v2, v16, 12, v2
	v_and_b32_e32 v3, 1, v17
	v_lshl_or_b32 v2, v3, 6, v2
	v_lshl_add_u32 v140, v18, 1, v2
	v_lshlrev_b32_e32 v2, 15, v13
	v_and_b32_e32 v2, 0xffff0000, v2
	s_waitcnt vmcnt(6)
	s_cmpk_lt_u32 s9, 0x100
	v_lshl_add_u32 v2, v14, 12, v2
	v_and_b32_e32 v3, 1, v13
	s_sext_i32_i8 s56, s8
	s_cselect_b64 s[8:9], -1, 0
	v_lshl_or_b32 v2, v3, 6, v2
	s_add_i32 s50, 0, 0x10000
	s_add_i32 s51, 0, 0x14000
	v_mov_b32_e32 v141, v135
	v_lshl_add_u32 v142, v15, 1, v2
	v_mov_b32_e32 v143, v135
	v_add_u32_e32 v149, s50, v147
	v_add_u32_e32 v150, s51, v147
	v_add_u32_e32 v151, 0, v5
	s_mov_b32 s52, 0x100000
	s_mov_b64 s[10:11], 0x120000
	s_mov_b32 s53, 0x120000
	s_mov_b64 s[12:13], 0x140000
	s_mov_b32 s54, 0x140000
	s_mov_b64 s[14:15], 0x160000
	s_mov_b32 s55, 0x160000
	s_barrier
	s_branch .LBB11_221

; #define PG8_STAGE(bufoff, gbase, voff) do { _Pragma("unroll") for (int _i = 0; _i < 2; ++_i) \
;         __builtin_amdgcn_global_load_lds((const unsigned*)((const char*)(gbase) + (voff)[_i]), (PG8_LAS unsigned*)(lds + (bufoff) + ldsw + _i * 8192), 16, 0, 0); } while (0)
; #define PG8_WAIT_V(n) asm volatile("s_waitcnt vmcnt(" #n ")" ::: "memory")
; #define PG8_BAR __builtin_amdgcn_s_barrier()
; template <class Epi, class Sched, bool ALIGN_EPI = false, bool SP2 = false>
; __device__ __forceinline__ void gemm_phase(PG8_LAS unsigned char* lds, const Gemm g, const Sched& S, const Epi& E) {
;     ...
;     for (int i = 0; i < 2; ++i) { int R, C; stage_rc(tid * 16 + i * 8192, R, C); const int Rb = Epi::PERM ? ((R & ~31) + perm32(R & 31)) : R;
;         voffA[i] = (unsigned)(R * K + C) * 2u; voffB[i] = (unsigned)(Rb * K + C) * 2u; }
;     const size_t kstep = (size_t)(BK * 2);
;     const size_t hstep = (size_t)HALF * K * 2;
;     const size_t tstep = 2 * hstep;
;     const unsigned ldsw = (unsigned)wid * 1024u;
;     const int aoff = lds_byte(wr * 64 + fr, fq * 8), boff = lds_byte(wc * 32 + fr, fq * 8);
;     ...
;     if constexpr (SP2) {
;         PG8_STAGE(PG8_SB(0, 0), cB, voffB); PG8_STAGE(PG8_SB(0, 1), cB + hstep, voffB); PG8_STAGE(PG8_SA(0, 0), cA, voffA); PG8_STAGE(PG8_SA(0, 1), cA + hstep, voffA);
;         if (wr == 1) PG8_BAR;
;         PG8_WAIT_V(2); PG8_BAR;
;         PG8_STAGE(PG8_SB(1, 0), cB + kstep, voffB); PG8_STAGE(PG8_SA(1, 0), cA + kstep, voffA); PG8_STAGE(PG8_SB(1, 1), cB + hstep + kstep, voffB);
;         PG8_WAIT_V(6); PG8_BAR;
.LBB11_450:
	s_lshl_b32 s8, s8, 5
	s_and_b32 s11, s8, 0x60
	s_mov_b64 s[8:9], 0x80
	s_add_i32 m0, s29, 0x18000
	v_lshl_add_u64 v[6:7], v[6:7], 0, s[8:9]
	global_load_lds_dwordx4 v[6:7], off
	v_lshl_add_u64 v[6:7], v[8:9], 0, s[8:9]
	s_add_i32 m0, s29, 0x1a000
	s_add_i32 s39, s29, 0x8000
	s_lshl_b32 s10, s7, 13
	s_lshl_b32 s12, s11, 7
	global_load_lds_dwordx4 v[6:7], off
	v_lshl_add_u64 v[6:7], v[10:11], 0, s[8:9]
	s_mov_b32 m0, s39
	s_add_i32 s40, s29, 0xa000
	global_load_lds_dwordx4 v[6:7], off
	v_lshl_add_u64 v[6:7], v[12:13], 0, s[8:9]
	s_add_u32 s8, s18, 0x80080
	s_mov_b32 m0, s40
	s_addc_u32 s9, s19, 0
	global_load_lds_dwordx4 v[6:7], off
	s_add_i32 m0, s29, 0x1c000
	v_lshl_add_u64 v[6:7], s[8:9], 0, v[2:3]
	global_load_lds_dwordx4 v[6:7], off
	v_lshl_add_u64 v[6:7], s[8:9], 0, v[132:133]
	s_add_i32 m0, s29, 0x1e000
	s_mov_b64 s[8:9], 0x4da00000
	global_load_lds_dwordx4 v[6:7], off
	s_waitcnt vmcnt(8)
	s_barrier
	v_lshl_add_u64 v[138:139], v[4:5], 0, s[8:9]
	v_lshrrev_b32_e32 v5, 1, v14
	v_and_b32_e32 v5, 24, v5
	v_and_b32_e32 v4, 15, v14
	v_lshlrev_b32_e32 v6, 1, v5
	v_lshl_or_b32 v146, s7, 6, v4
	v_lshl_or_b32 v4, v4, 6, v6
	v_lshlrev_b32_e32 v6, 2, v14
	v_and_b32_e32 v6, 32, v6
	v_bitop3_b32 v7, v4, s10, v6 bitop3:0xde
	v_bitop3_b32 v147, v4, s12, v6 bitop3:0xde
	v_lshlrev_b32_e32 v4, 15, v19
	v_and_b32_e32 v4, 0xffff0000, v4
	v_or_b32_e32 v148, s11, v5
	v_lshl_add_u32 v4, v18, 12, v4
	v_and_b32_e32 v5, 1, v19
	v_lshl_or_b32 v4, v5, 6, v4
	v_lshl_add_u32 v140, v20, 1, v4
	v_lshlrev_b32_e32 v4, 15, v15
	v_and_b32_e32 v4, 0xffff0000, v4
	s_waitcnt vmcnt(6)
	v_lshl_add_u32 v4, v16, 12, v4
	v_and_b32_e32 v5, 1, v15
	s_cmpk_lt_u32 s6, 0x100
	v_lshl_or_b32 v4, v5, 6, v4
	v_readlane_b32 s8, v251, 35
	s_cselect_b64 s[6:7], -1, 0
	v_mov_b32_e32 v141, v3
	v_lshl_add_u32 v142, v17, 1, v4
	v_mov_b32_e32 v143, v3
	s_mov_b32 s41, 0
	v_add_u32_e32 v149, 0, v7
	v_readlane_b32 s42, v251, 32
	s_mov_b32 s43, s8
	s_barrier
	v_readlane_b32 s9, v251, 36
	s_branch .LBB11_453

; #define PG8_STAGE(bufoff, gbase, voff) do { _Pragma("unroll") for (int _i = 0; _i < 2; ++_i) \
;         __builtin_amdgcn_global_load_lds((const unsigned*)((const char*)(gbase) + (voff)[_i]), (PG8_LAS unsigned*)(lds + (bufoff) + ldsw + _i * 8192), 16, 0, 0); } while (0)
; #define PG8_WAIT_V(n) asm volatile("s_waitcnt vmcnt(" #n ")" ::: "memory")
; #define PG8_BAR __builtin_amdgcn_s_barrier()
; template <class Epi, class Sched, bool ALIGN_EPI = false, bool SP2 = false>
; __device__ __forceinline__ void gemm_phase(PG8_LAS unsigned char* lds, const Gemm g, const Sched& S, const Epi& E) {
;     ...
;     for (int i = 0; i < 2; ++i) { int R, C; stage_rc(tid * 16 + i * 8192, R, C); const int Rb = Epi::PERM ? ((R & ~31) + perm32(R & 31)) : R;
;         voffA[i] = (unsigned)(R * K + C) * 2u; voffB[i] = (unsigned)(Rb * K + C) * 2u; }
;     const size_t kstep = (size_t)(BK * 2);
;     const size_t hstep = (size_t)HALF * K * 2;
;     const size_t tstep = 2 * hstep;
;     const unsigned ldsw = (unsigned)wid * 1024u;
;     const int aoff = lds_byte(wr * 64 + fr, fq * 8), boff = lds_byte(wc * 32 + fr, fq * 8);
;     ...
;     if constexpr (SP2) {
;         PG8_STAGE(PG8_SB(0, 0), cB, voffB); PG8_STAGE(PG8_SB(0, 1), cB + hstep, voffB); PG8_STAGE(PG8_SA(0, 0), cA, voffA); PG8_STAGE(PG8_SA(0, 1), cA + hstep, voffA);
;         if (wr == 1) PG8_BAR;
;         PG8_WAIT_V(2); PG8_BAR;
;         PG8_STAGE(PG8_SB(1, 0), cB + kstep, voffB); PG8_STAGE(PG8_SA(1, 0), cA + kstep, voffA); PG8_STAGE(PG8_SB(1, 1), cB + hstep + kstep, voffB);
;         PG8_WAIT_V(6); PG8_BAR;
.LBB11_628:
	s_lshl_b32 s8, s8, 5
	s_and_b32 s11, s8, 0x60
	s_mov_b64 s[8:9], 0x80
	s_add_i32 m0, s33, 0x18000
	v_lshl_add_u64 v[6:7], v[6:7], 0, s[8:9]
	global_load_lds_dwordx4 v[6:7], off
	v_lshl_add_u64 v[6:7], v[8:9], 0, s[8:9]
	s_add_i32 m0, s33, 0x1a000
	s_add_i32 s39, s33, 0x8000
	s_lshl_b32 s10, s5, 13
	s_lshl_b32 s12, s11, 7
	global_load_lds_dwordx4 v[6:7], off
	v_lshl_add_u64 v[6:7], v[10:11], 0, s[8:9]
	s_mov_b32 m0, s39
	s_add_i32 s40, s33, 0xa000
	global_load_lds_dwordx4 v[6:7], off
	v_lshl_add_u64 v[6:7], v[12:13], 0, s[8:9]
	s_add_u32 s8, s20, 0x80080
	s_mov_b32 m0, s40
	s_addc_u32 s9, s21, 0
	global_load_lds_dwordx4 v[6:7], off
	s_add_i32 m0, s33, 0x1c000
	v_lshl_add_u64 v[6:7], s[8:9], 0, v[2:3]
	global_load_lds_dwordx4 v[6:7], off
	v_lshl_add_u64 v[6:7], s[8:9], 0, v[132:133]
	s_add_i32 m0, s33, 0x1e000
	s_mov_b64 s[8:9], 0x5b200000
	global_load_lds_dwordx4 v[6:7], off
	s_waitcnt vmcnt(8)
	s_barrier
	v_lshl_add_u64 v[138:139], v[4:5], 0, s[8:9]
	v_lshrrev_b32_e32 v5, 1, v14
	v_and_b32_e32 v5, 24, v5
	v_and_b32_e32 v4, 15, v14
	v_lshlrev_b32_e32 v6, 1, v5
	v_lshl_or_b32 v146, s5, 6, v4
	v_lshl_or_b32 v4, v4, 6, v6
	v_lshlrev_b32_e32 v6, 2, v14
	v_and_b32_e32 v6, 32, v6
	v_bitop3_b32 v7, v4, s10, v6 bitop3:0xde
	v_bitop3_b32 v147, v4, s12, v6 bitop3:0xde
	v_lshlrev_b32_e32 v4, 15, v19
	v_and_b32_e32 v4, 0xffff0000, v4
	v_or_b32_e32 v148, s11, v5
	v_lshl_add_u32 v4, v18, 12, v4
	v_and_b32_e32 v5, 1, v19
	v_lshl_or_b32 v4, v5, 6, v4
	v_lshl_add_u32 v140, v20, 1, v4
	v_lshlrev_b32_e32 v4, 15, v15
	v_and_b32_e32 v4, 0xffff0000, v4
	s_waitcnt vmcnt(6)
	v_lshl_add_u32 v4, v16, 12, v4
	v_and_b32_e32 v5, 1, v15
	s_cmpk_lt_u32 s4, 0x100
	v_lshl_or_b32 v4, v5, 6, v4
	v_readlane_b32 s8, v251, 62
	s_cselect_b64 s[4:5], -1, 0
	v_mov_b32_e32 v141, v3
	v_lshl_add_u32 v142, v17, 1, v4
	v_mov_b32_e32 v143, v3
	s_mov_b32 s41, 0
	v_add_u32_e32 v149, 0, v7
	v_readlane_b32 s42, v251, 48
	s_mov_b32 s43, s8
	s_barrier
	v_readlane_b32 s9, v251, 63
	s_branch .LBB11_631

; #define PG8_STAGE(bufoff, gbase, voff) do { _Pragma("unroll") for (int _i = 0; _i < 2; ++_i) \
;         __builtin_amdgcn_global_load_lds((const unsigned*)((const char*)(gbase) + (voff)[_i]), (PG8_LAS unsigned*)(lds + (bufoff) + ldsw + _i * 8192), 16, 0, 0); } while (0)
; #define PG8_WAIT_V(n) asm volatile("s_waitcnt vmcnt(" #n ")" ::: "memory")
; #define PG8_BAR __builtin_amdgcn_s_barrier()
; template <class Epi, class Sched, bool ALIGN_EPI = false, bool SP2 = false>
; __device__ __forceinline__ void gemm_phase(PG8_LAS unsigned char* lds, const Gemm g, const Sched& S, const Epi& E) {
;     ...
;     for (int i = 0; i < 2; ++i) { int R, C; stage_rc(tid * 16 + i * 8192, R, C); const int Rb = Epi::PERM ? ((R & ~31) + perm32(R & 31)) : R;
;         voffA[i] = (unsigned)(R * K + C) * 2u; voffB[i] = (unsigned)(Rb * K + C) * 2u; }
;     const size_t kstep = (size_t)(BK * 2);
;     const size_t hstep = (size_t)HALF * K * 2;
;     const size_t tstep = 2 * hstep;
;     const unsigned ldsw = (unsigned)wid * 1024u;
;     const int aoff = lds_byte(wr * 64 + fr, fq * 8), boff = lds_byte(wc * 32 + fr, fq * 8);
;     ...
;     if constexpr (SP2) {
;         PG8_STAGE(PG8_SB(0, 0), cB, voffB); PG8_STAGE(PG8_SB(0, 1), cB + hstep, voffB); PG8_STAGE(PG8_SA(0, 0), cA, voffA); PG8_STAGE(PG8_SA(0, 1), cA + hstep, voffA);
;         if (wr == 1) PG8_BAR;
;         PG8_WAIT_V(2); PG8_BAR;
;         PG8_STAGE(PG8_SB(1, 0), cB + kstep, voffB); PG8_STAGE(PG8_SA(1, 0), cA + kstep, voffA); PG8_STAGE(PG8_SB(1, 1), cB + hstep + kstep, voffB);
;         PG8_WAIT_V(6); PG8_BAR;
.LBB11_907:
	s_lshl_b32 s6, s6, 5
	s_and_b32 s9, s6, 0x60
	s_mov_b64 s[6:7], 0x80
	s_add_i32 m0, s24, 0x18000
	v_lshl_add_u64 v[6:7], v[6:7], 0, s[6:7]
	global_load_lds_dwordx4 v[6:7], off
	v_lshl_add_u64 v[6:7], v[8:9], 0, s[6:7]
	s_add_i32 m0, s24, 0x1a000
	s_add_i32 s28, s24, 0x8000
	s_lshl_b32 s8, s5, 13
	s_lshl_b32 s10, s9, 7
	global_load_lds_dwordx4 v[6:7], off
	v_lshl_add_u64 v[6:7], v[10:11], 0, s[6:7]
	s_mov_b32 m0, s28
	s_add_i32 s29, s24, 0xa000
	global_load_lds_dwordx4 v[6:7], off
	v_lshl_add_u64 v[6:7], v[12:13], 0, s[6:7]
	s_add_u32 s6, s16, 0x80080
	s_mov_b32 m0, s29
	s_addc_u32 s7, s17, 0
	global_load_lds_dwordx4 v[6:7], off
	s_add_i32 m0, s24, 0x1c000
	v_lshl_add_u64 v[6:7], s[6:7], 0, v[2:3]
	global_load_lds_dwordx4 v[6:7], off
	v_lshl_add_u64 v[6:7], s[6:7], 0, v[132:133]
	s_add_i32 m0, s24, 0x1e000
	s_mov_b64 s[6:7], 0x53200000
	global_load_lds_dwordx4 v[6:7], off
	s_waitcnt vmcnt(8)
	s_barrier
	v_lshl_add_u64 v[138:139], v[4:5], 0, s[6:7]
	v_lshrrev_b32_e32 v5, 1, v14
	v_and_b32_e32 v5, 24, v5
	v_and_b32_e32 v4, 15, v14
	v_lshlrev_b32_e32 v6, 1, v5
	v_lshl_or_b32 v1, s5, 6, v4
	v_lshl_or_b32 v4, v4, 6, v6
	v_lshlrev_b32_e32 v6, 2, v14
	v_and_b32_e32 v6, 32, v6
	v_bitop3_b32 v7, v4, s8, v6 bitop3:0xde
	v_bitop3_b32 v146, v4, s10, v6 bitop3:0xde
	v_lshlrev_b32_e32 v4, 15, v19
	v_and_b32_e32 v4, 0xffff0000, v4
	v_or_b32_e32 v147, s9, v5
	v_lshl_add_u32 v4, v18, 12, v4
	v_and_b32_e32 v5, 1, v19
	v_lshl_or_b32 v4, v5, 6, v4
	v_lshl_add_u32 v140, v20, 1, v4
	v_lshlrev_b32_e32 v4, 15, v15
	v_and_b32_e32 v4, 0xffff0000, v4
	s_waitcnt vmcnt(6)
	v_lshl_add_u32 v4, v16, 12, v4
	v_and_b32_e32 v5, 1, v15
	s_cmpk_lt_u32 s4, 0x100
	v_lshl_or_b32 v4, v5, 6, v4
	v_readlane_b32 s6, v252, 2
	s_cselect_b64 s[4:5], -1, 0
	v_mov_b32_e32 v141, v3
	v_lshl_add_u32 v142, v17, 1, v4
	v_mov_b32_e32 v143, v3
	s_mov_b32 s30, 0
	v_add_u32_e32 v148, 0, v7
	v_readlane_b32 s33, v251, 51
	s_mov_b32 s36, s6
	s_barrier
	v_readlane_b32 s7, v252, 3
	s_branch .LBB11_910

; #define PG8_STAGE(bufoff, gbase, voff) do { _Pragma("unroll") for (int _i = 0; _i < 2; ++_i) \
;         __builtin_amdgcn_global_load_lds((const unsigned*)((const char*)(gbase) + (voff)[_i]), (PG8_LAS unsigned*)(lds + (bufoff) + ldsw + _i * 8192), 16, 0, 0); } while (0)
; #define PG8_WAIT_V(n) asm volatile("s_waitcnt vmcnt(" #n ")" ::: "memory")
; #define PG8_BAR __builtin_amdgcn_s_barrier()
; template <class Epi, class Sched, bool ALIGN_EPI = false, bool SP2 = false>
; __device__ __forceinline__ void gemm_phase(PG8_LAS unsigned char* lds, const Gemm g, const Sched& S, const Epi& E) {
;     ...
;     for (int i = 0; i < 2; ++i) { int R, C; stage_rc(tid * 16 + i * 8192, R, C); const int Rb = Epi::PERM ? ((R & ~31) + perm32(R & 31)) : R;
;         voffA[i] = (unsigned)(R * K + C) * 2u; voffB[i] = (unsigned)(Rb * K + C) * 2u; }
;     const size_t kstep = (size_t)(BK * 2);
;     const size_t hstep = (size_t)HALF * K * 2;
;     const size_t tstep = 2 * hstep;
;     const unsigned ldsw = (unsigned)wid * 1024u;
;     const int aoff = lds_byte(wr * 64 + fr, fq * 8), boff = lds_byte(wc * 32 + fr, fq * 8);
;     ...
;     if constexpr (SP2) {
;         PG8_STAGE(PG8_SB(0, 0), cB, voffB); PG8_STAGE(PG8_SB(0, 1), cB + hstep, voffB); PG8_STAGE(PG8_SA(0, 0), cA, voffA); PG8_STAGE(PG8_SA(0, 1), cA + hstep, voffA);
;         if (wr == 1) PG8_BAR;
;         PG8_WAIT_V(2); PG8_BAR;
;         PG8_STAGE(PG8_SB(1, 0), cB + kstep, voffB); PG8_STAGE(PG8_SA(1, 0), cA + kstep, voffA); PG8_STAGE(PG8_SB(1, 1), cB + hstep + kstep, voffB);
;         PG8_WAIT_V(6); PG8_BAR;
.LBB11_1065:
	s_and_b32 s29, s6, 3
	s_mov_b64 s[6:7], 0x80
	s_add_i32 m0, s25, 0x18000
	v_lshl_add_u64 v[4:5], v[4:5], 0, s[6:7]
	global_load_lds_dwordx4 v[4:5], off
	v_lshl_add_u64 v[4:5], v[6:7], 0, s[6:7]
	s_add_i32 m0, s25, 0x1a000
	s_add_i32 s33, s25, 0x8000
	s_lshl_b32 s8, s5, 13
	s_lshl_b32 s9, s29, 12
	global_load_lds_dwordx4 v[4:5], off
	v_lshl_add_u64 v[4:5], v[8:9], 0, s[6:7]
	s_mov_b32 m0, s33
	s_add_i32 s38, s25, 0xa000
	global_load_lds_dwordx4 v[4:5], off
	v_lshl_add_u64 v[4:5], v[10:11], 0, s[6:7]
	s_add_u32 s6, s16, 0x80080
	s_mov_b32 m0, s38
	s_addc_u32 s7, s17, 0
	global_load_lds_dwordx4 v[4:5], off
	s_add_i32 m0, s25, 0x1c000
	v_lshl_add_u64 v[4:5], s[6:7], 0, v[154:155]
	global_load_lds_dwordx4 v[4:5], off
	v_lshl_add_u64 v[4:5], s[6:7], 0, v[150:151]
	s_add_i32 m0, s25, 0x1e000
	s_mov_b64 s[6:7], 0x53200000
	global_load_lds_dwordx4 v[4:5], off
	s_waitcnt vmcnt(8)
	s_barrier
	v_lshrrev_b32_e32 v5, 1, v2
	v_and_b32_e32 v5, 24, v5
	v_and_b32_e32 v4, 15, v2
	v_lshlrev_b32_e32 v6, 1, v5
	v_lshlrev_b32_e32 v2, 2, v2
	v_lshl_or_b32 v161, s5, 6, v4
	v_lshl_or_b32 v4, v4, 6, v6
	v_and_b32_e32 v2, 32, v2
	v_bitop3_b32 v6, v4, s8, v2 bitop3:0xde
	s_waitcnt vmcnt(0)
	v_bitop3_b32 v168, v4, s9, v2 bitop3:0xde
	v_lshlrev_b32_e32 v2, 15, v16
	v_and_b32_e32 v2, 0xffff0000, v2
	v_lshl_add_u32 v2, v15, 12, v2
	v_and_b32_e32 v4, 1, v16
	v_lshl_or_b32 v2, v4, 6, v2
	v_lshl_add_u32 v162, v17, 1, v2
	v_lshlrev_b32_e32 v2, 15, v12
	v_and_b32_e32 v2, 0xffff0000, v2
	s_waitcnt vmcnt(6)
	v_lshl_add_u32 v2, v13, 12, v2
	v_and_b32_e32 v4, 1, v12
	v_lshl_add_u64 v[158:159], v[148:149], 0, s[6:7]
	s_cmpk_lt_u32 s4, 0x100
	v_lshl_or_b32 v2, v4, 6, v2
	v_readlane_b32 s6, v251, 23
	s_cselect_b64 s[4:5], -1, 0
	v_lshl_or_b32 v160, s29, 5, v5
	v_mov_b32_e32 v163, v3
	v_lshl_add_u32 v164, v14, 1, v2
	v_mov_b32_e32 v165, v3
	s_mov_b32 s39, 0
	v_add_u32_e32 v169, 0, v6
	v_readlane_b32 s40, v251, 20
	s_mov_b32 s30, s6
	s_barrier
	v_readlane_b32 s7, v251, 24
	s_branch .LBB11_1068

; #define PG8_STAGE(bufoff, gbase, voff) do { _Pragma("unroll") for (int _i = 0; _i < 2; ++_i) \
;         __builtin_amdgcn_global_load_lds((const unsigned*)((const char*)(gbase) + (voff)[_i]), (PG8_LAS unsigned*)(lds + (bufoff) + ldsw + _i * 8192), 16, 0, 0); } while (0)
; #define PG8_WAIT_V(n) asm volatile("s_waitcnt vmcnt(" #n ")" ::: "memory")
; #define PG8_BAR __builtin_amdgcn_s_barrier()
; template <class Epi, class Sched, bool ALIGN_EPI = false, bool SP2 = false>
; __device__ __forceinline__ void gemm_phase(PG8_LAS unsigned char* lds, const Gemm g, const Sched& S, const Epi& E) {
;     ...
;     f32x4 acc[2][2][4][2];
; #pragma unroll
;     for (int a = 0; a < 2; ++a)
; #pragma unroll
;         for (int b = 0; b < 2; ++b)
; #pragma unroll
;             for (int m = 0; m < 4; ++m)
; #pragma unroll
;                 for (int n = 0; n < 2; ++n) acc[a][b][m][n] = (f32x4){0.f, 0.f, 0.f, 0.f};
;     ...
;     if constexpr (SP2) {
;         PG8_STAGE(PG8_SB(0, 0), cB, voffB); PG8_STAGE(PG8_SB(0, 1), cB + hstep, voffB); PG8_STAGE(PG8_SA(0, 0), cA, voffA); PG8_STAGE(PG8_SA(0, 1), cA + hstep, voffA);
;         if (wr == 1) PG8_BAR;
;         PG8_WAIT_V(2); PG8_BAR;
;         PG8_STAGE(PG8_SB(1, 0), cB + kstep, voffB); PG8_STAGE(PG8_SA(1, 0), cA + kstep, voffA); PG8_STAGE(PG8_SB(1, 1), cB + hstep + kstep, voffB);
;         PG8_WAIT_V(6); PG8_BAR;
.LBB11_1883:
	v_mov_b32_e32 v133, v3
	v_and_b32_e32 v165, 15, v142
	v_and_b32_e32 v1, 48, v142
	v_lshlrev_b32_e32 v22, 2, v142
	v_lshl_add_u64 v[14:15], s[4:5], 0, v[2:3]
	v_lshl_add_u64 v[16:17], s[4:5], 0, v[132:133]
	s_and_b32 s43, s25, 3
	s_lshl_b32 s4, s30, 13
	v_lshl_or_b32 v1, v165, 6, v1
	v_and_b32_e32 v22, 32, v22
	v_bitop3_b32 v23, v1, s4, v22 bitop3:0xde
	s_lshl_b32 s4, s43, 12
	v_lshl_add_u64 v[10:11], s[14:15], 0, v[2:3]
	v_bitop3_b32 v1, v1, s4, v22 bitop3:0xde
	s_mov_b64 s[4:5], 0x80
	v_lshl_add_u64 v[12:13], s[14:15], 0, v[132:133]
	s_add_i32 m0, s45, 0x18000
	v_lshl_add_u64 v[10:11], v[10:11], 0, s[4:5]
	v_lshl_add_u64 v[18:19], s[16:17], 0, v[2:3]
	global_load_lds_dwordx4 v[10:11], off
	v_lshl_add_u64 v[10:11], v[12:13], 0, s[4:5]
	s_add_i32 m0, s45, 0x1a000
	s_add_i32 s50, s45, 0x8000
	v_lshl_add_u64 v[20:21], s[16:17], 0, v[132:133]
	global_load_lds_dwordx4 v[10:11], off
	v_lshl_add_u64 v[10:11], v[18:19], 0, s[4:5]
	s_mov_b32 m0, s50
	s_add_i32 s51, s45, 0xa000
	global_load_lds_dwordx4 v[10:11], off
	v_lshl_add_u64 v[10:11], v[20:21], 0, s[4:5]
	s_mov_b32 m0, s51
	s_lshr_b32 s29, s29, 6
	global_load_lds_dwordx4 v[10:11], off
	s_add_i32 m0, s45, 0x1c000
	v_lshl_add_u64 v[10:11], v[14:15], 0, s[4:5]
	global_load_lds_dwordx4 v[10:11], off
	v_lshl_add_u64 v[10:11], v[16:17], 0, s[4:5]
	s_add_i32 m0, s45, 0x1e000
	s_lshl_b32 s1, s30, 6
	global_load_lds_dwordx4 v[10:11], off
	s_waitcnt vmcnt(8)
	s_barrier
	s_add_i32 s49, s29, -2
	s_add_u32 s4, s33, 0x80
	v_add_u32_e32 v7, v7, v8
	v_add_u32_e32 v4, v4, v5
	s_waitcnt vmcnt(6)
	s_addc_u32 s5, 0, 0
	v_add_lshl_u32 v8, v7, v9, 1
	v_mov_b32_e32 v9, v3
	v_add_lshl_u32 v4, v4, v6, 1
	v_mov_b32_e32 v5, v3
	v_lshl_add_u64 v[134:135], s[4:5], 0, v[8:9]
	v_lshl_add_u64 v[136:137], s[4:5], 0, v[4:5]
	v_mov_b32_e32 v20, 0
	v_readlane_b32 s4, v251, 54
	v_or_b32_e32 v164, s1, v165
	s_mov_b32 s52, 0
	v_add_u32_e32 v143, 0, v23
	s_mov_b32 s42, s4
	v_readlane_b32 s28, v251, 47
	v_mov_b32_e32 v21, v20
	v_mov_b32_e32 v22, v20
	v_mov_b32_e32 v23, v20
	v_mov_b32_e32 v28, v20
	v_mov_b32_e32 v29, v20
	v_mov_b32_e32 v30, v20
	v_mov_b32_e32 v31, v20
	v_mov_b32_e32 v52, v20
	v_mov_b32_e32 v53, v20
	v_mov_b32_e32 v54, v20
	v_mov_b32_e32 v55, v20
	v_mov_b32_e32 v56, v20
	v_mov_b32_e32 v57, v20
	v_mov_b32_e32 v58, v20
	v_mov_b32_e32 v59, v20
	v_mov_b32_e32 v72, v20
	v_mov_b32_e32 v73, v20
	v_mov_b32_e32 v74, v20
	v_mov_b32_e32 v75, v20
	v_mov_b32_e32 v84, v20
	v_mov_b32_e32 v85, v20
	v_mov_b32_e32 v86, v20
	v_mov_b32_e32 v87, v20
	v_mov_b32_e32 v44, v20
	v_mov_b32_e32 v45, v20
	v_mov_b32_e32 v46, v20
	v_mov_b32_e32 v47, v20
	v_mov_b32_e32 v96, v20
	v_mov_b32_e32 v97, v20
	v_mov_b32_e32 v98, v20
	v_mov_b32_e32 v99, v20
	v_mov_b32_e32 v40, v20
	v_mov_b32_e32 v41, v20
	v_mov_b32_e32 v42, v20
	v_mov_b32_e32 v43, v20
	v_mov_b32_e32 v36, v20
	v_mov_b32_e32 v37, v20
	v_mov_b32_e32 v38, v20
	v_mov_b32_e32 v39, v20
	v_mov_b32_e32 v64, v20
	v_mov_b32_e32 v65, v20
	v_mov_b32_e32 v66, v20
	v_mov_b32_e32 v67, v20
	v_mov_b32_e32 v60, v20
	v_mov_b32_e32 v61, v20
	v_mov_b32_e32 v62, v20
	v_mov_b32_e32 v63, v20
	v_mov_b32_e32 v92, v20
	v_mov_b32_e32 v93, v20
	v_mov_b32_e32 v94, v20
	v_mov_b32_e32 v95, v20
	v_mov_b32_e32 v88, v20
	v_mov_b32_e32 v89, v20
	v_mov_b32_e32 v90, v20
	v_mov_b32_e32 v91, v20
	v_mov_b32_e32 v112, v20
	v_mov_b32_e32 v113, v20
	v_mov_b32_e32 v114, v20
	v_mov_b32_e32 v115, v20
	v_mov_b32_e32 v108, v20
	v_mov_b32_e32 v109, v20
	v_mov_b32_e32 v110, v20
	v_mov_b32_e32 v111, v20
	v_mov_b32_e32 v24, v20
	v_mov_b32_e32 v25, v20
	v_mov_b32_e32 v26, v20
	v_mov_b32_e32 v27, v20
	v_mov_b32_e32 v76, v20
	v_mov_b32_e32 v77, v20
	v_mov_b32_e32 v78, v20
	v_mov_b32_e32 v79, v20
	v_mov_b32_e32 v12, v20
	v_mov_b32_e32 v13, v20
	v_mov_b32_e32 v14, v20
	v_mov_b32_e32 v15, v20
	v_mov_b32_e32 v48, v20
	v_mov_b32_e32 v49, v20
	v_mov_b32_e32 v50, v20
	v_mov_b32_e32 v51, v20
	v_mov_b32_e32 v8, v20
	v_mov_b32_e32 v9, v20
	v_mov_b32_e32 v10, v20
	v_mov_b32_e32 v11, v20
	v_mov_b32_e32 v32, v20
	v_mov_b32_e32 v33, v20
	v_mov_b32_e32 v34, v20
	v_mov_b32_e32 v35, v20
	v_mov_b32_e32 v4, v20
	v_mov_b32_e32 v5, v20
	v_mov_b32_e32 v6, v20
	v_mov_b32_e32 v7, v20
	v_mov_b32_e32 v16, v20
	v_mov_b32_e32 v17, v20
	v_mov_b32_e32 v18, v20
	v_mov_b32_e32 v19, v20
	v_mov_b32_e32 v120, v20
	v_mov_b32_e32 v121, v20
	v_mov_b32_e32 v122, v20
	v_mov_b32_e32 v123, v20
	v_mov_b32_e32 v128, v20
	v_mov_b32_e32 v129, v20
	v_mov_b32_e32 v130, v20
	v_mov_b32_e32 v131, v20
	v_mov_b32_e32 v104, v20
	v_mov_b32_e32 v105, v20
	v_mov_b32_e32 v106, v20
	v_mov_b32_e32 v107, v20
	v_mov_b32_e32 v124, v20
	v_mov_b32_e32 v125, v20
	v_mov_b32_e32 v126, v20
	v_mov_b32_e32 v127, v20
	v_mov_b32_e32 v80, v20
	v_mov_b32_e32 v81, v20
	v_mov_b32_e32 v82, v20
	v_mov_b32_e32 v83, v20
	v_mov_b32_e32 v116, v20
	v_mov_b32_e32 v117, v20
	v_mov_b32_e32 v118, v20
	v_mov_b32_e32 v119, v20
	v_mov_b32_e32 v68, v20
	v_mov_b32_e32 v69, v20
	v_mov_b32_e32 v70, v20
	v_mov_b32_e32 v71, v20
	v_mov_b32_e32 v100, v20
	v_mov_b32_e32 v101, v20
	v_mov_b32_e32 v102, v20
	v_mov_b32_e32 v103, v20
	s_barrier
	s_branch .LBB11_1885
